# input-projection epilogue: eight row-statistic loads issued together at the first row group (on top of the FFN2 gate/up epilogue change)
# baseline (speedup 1.0000x reference)
; __device__ __forceinline__ float fsigmoid(float x) { return __builtin_amdgcn_rcpf(1.0f + __builtin_amdgcn_exp2f(-1.4426950408889634f * x)); }
; __device__ __forceinline__ float fsilu(float x) { return x * fsigmoid(x); }
;     __device__ __forceinline__ void operator()(const f32x4 (&acc)[2][2][4][2], const Unit& u, int wr, int wc, int fr, int fq) const {
;     ...
; #pragma unroll
;         for (int ai = 0; ai < 2; ++ai)
; #pragma unroll
;             for (int m = 0; m < 4; ++m) {
;                 const int r = u.pm * BM + ai * HALF + wr * 64 + m * 16 + fr;
;                 if (u.pm * BM + ai * HALF + wr * 64 + m * 16 >= 16400) continue;
;                 const int drow = espace ? (r < 16384 ? r + 64 : r - 16384 + 48) : r;
;                 const float rs = 1.0f / sqrtf(stat[r] * (1.0f / 4096.0f) + 1e-6f);
; #pragma unroll
;                 for (int bj = 0; bj < 2; ++bj) {
;                     const int c = bj * HALF + wc * 32 + 8 * fq;
;                     if (pn == 38 && c >= 64) continue;
;                     const f32x4 v0 = acc[ai][bj][m][0] * rs, v1 = acc[ai][bj][m][1] * rs;
;                     if (mode == 2) {
;                         const f32x4 l0 = *(const f32x4*)(lb + cbase + c), l1 = *(const f32x4*)(lb + cbase + c + 4); f32x4 o0, o1;
; #pragma unroll
;                         for (int j = 0; j < 4; ++j) { o0[j] = __logf(l0[j] + (1.0f - l0[j]) * fsigmoid(v0[j])); o1[j] = __logf(l1[j] + (1.0f - l1[j]) * fsigmoid(v1[j])); }
;                         float* p = LOGF + (size_t)drow * ld + cbase + c; *(f32x4*)p = o0; *(f32x4*)(p + 4) = o1;
;                     } else {
;                         u32x4 w;
;                         if (mode == 1) { w.x = pk_bf16(fsilu(v0[0]), fsilu(v0[1])); w.y = pk_bf16(fsilu(v0[2]), fsilu(v0[3])); w.z = pk_bf16(fsilu(v1[0]), fsilu(v1[1])); w.w = pk_bf16(fsilu(v1[2]), fsilu(v1[3])); }
;                         else { w.x = pk_bf16(v0[0], v0[1]); w.y = pk_bf16(v0[2], v0[3]); w.z = pk_bf16(v1[0], v1[1]); w.w = pk_bf16(v1[2], v1[3]); }
.LBB0_384:
	v_ashrrev_i32_e32 v131, 31, v130
	v_lshl_add_u64 v[130:131], v[130:131], 2, s[14:15]
	global_load_dword v200, v[130:131], off offset:64
	global_load_dword v201, v[130:131], off offset:128
	global_load_dword v202, v[130:131], off offset:192
	global_load_dword v203, v[130:131], off offset:512
	global_load_dword v204, v[130:131], off offset:576
	global_load_dword v205, v[130:131], off offset:640
	global_load_dword v206, v[130:131], off offset:704
	global_load_dword v130, v[130:131], off
	s_waitcnt vmcnt(0)
	v_fmamk_f32 v130, v130, 0x39800000, v173
	v_cmp_gt_f32_e32 vcc, s95, v130
	v_mul_f32_e32 v131, 0x4f800000, v130
	s_nop 0
	v_cndmask_b32_e32 v130, v130, v131, vcc
	v_sqrt_f32_e32 v131, v130
	s_nop 0
	v_add_u32_e32 v156, -1, v131
	v_fma_f32 v157, -v156, v131, v130
	v_cmp_ge_f32_e64 s[6:7], 0, v157
	v_add_u32_e32 v157, 1, v131
	s_nop 0
	v_cndmask_b32_e64 v156, v131, v156, s[6:7]
	v_fma_f32 v131, -v157, v131, v130
	v_cmp_lt_f32_e64 s[6:7], 0, v131
	s_nop 1
	v_cndmask_b32_e64 v131, v156, v157, s[6:7]
	v_mul_f32_e32 v156, 0x37800000, v131
	v_cndmask_b32_e32 v131, v131, v156, vcc
	v_cmp_class_f32_e32 vcc, v130, v174
	s_nop 1
	v_cndmask_b32_e32 v130, v131, v130, vcc
	v_div_scale_f32 v131, s[6:7], v130, v130, 1.0
	v_rcp_f32_e32 v156, v131
	s_nop 0
	v_fma_f32 v157, -v131, v156, 1.0
	v_fmac_f32_e32 v156, v157, v156
	v_div_scale_f32 v157, vcc, 1.0, v130, 1.0
	v_mul_f32_e32 v158, v157, v156
	v_fma_f32 v159, -v131, v158, v157
	v_fmac_f32_e32 v158, v159, v156
	v_fma_f32 v131, -v131, v158, v157
	v_div_fmas_f32 v131, v131, v156, v158
	v_div_fixup_f32 v160, v131, v130, 1.0
	v_ashrrev_i32_e32 v130, 31, v140
	v_mul_lo_u32 v131, s9, v140
	v_mul_lo_u32 v130, s8, v130
	v_mad_u64_u32 v[156:157], s[6:7], s8, v140, 0
	v_add3_u32 v157, v157, v130, v131
	s_and_b64 s[6:7], s[80:81], s[34:35]
	v_mov_b32_e32 v161, v160
	v_lshl_add_u64 v[158:159], v[156:157], 1, s[10:11]
	s_and_b64 vcc, exec, s[6:7]
	s_cbranch_vccnz .LBB0_393
	v_mov_b32_e32 v130, v160
	v_mov_b32_e32 v131, v160
	v_pk_mul_f32 v[164:165], v[128:129], v[130:131]
	v_pk_mul_f32 v[168:169], v[126:127], v[160:161]
	v_pk_mul_f32 v[162:163], v[124:125], v[130:131]
	v_pk_mul_f32 v[166:167], v[122:123], v[160:161]
	s_mov_b64 s[6:7], -1
	s_and_b64 vcc, exec, s[12:13]
	s_cbranch_vccz .LBB0_391
	s_and_b64 vcc, exec, s[58:59]
	s_cbranch_vccz .LBB0_388
	v_cvt_pk_bf16_f32 v122, v168, v169
	v_cvt_pk_bf16_f32 v123, v164, v165
	v_cvt_pk_bf16_f32 v124, v166, v167
	s_mov_b64 s[6:7], 0
	v_mov_b32_e32 v127, v163
	v_mov_b32_e32 v126, v162

;     __device__ __forceinline__ void operator()(const f32x4 (&acc)[2][2][4][2], const Unit& u, int wr, int wc, int fr, int fq) const {
;     ...
;             for (int m = 0; m < 4; ++m) {
;                 const int r = u.pm * BM + ai * HALF + wr * 64 + m * 16 + fr;
;                 if (u.pm * BM + ai * HALF + wr * 64 + m * 16 >= 16400) continue;
;                 const int drow = espace ? (r < 16384 ? r + 64 : r - 16384 + 48) : r;
;                 const float rs = 1.0f / sqrtf(stat[r] * (1.0f / 4096.0f) + 1e-6f);
; #pragma unroll
;                 for (int bj = 0; bj < 2; ++bj) {
;                     const int c = bj * HALF + wc * 32 + 8 * fq;
;                     if (pn == 38 && c >= 64) continue;
;                     const f32x4 v0 = acc[ai][bj][m][0] * rs, v1 = acc[ai][bj][m][1] * rs;
.LBB0_409:
	v_ashrrev_i32_e32 v115, 31, v114
	v_lshl_add_u64 v[114:115], v[114:115], 2, s[14:15]
	s_nop 1
	v_mov_b32_e32 v114, v200
	v_fmamk_f32 v114, v114, 0x39800000, v173
	v_cmp_gt_f32_e32 vcc, s95, v114
	v_mul_f32_e32 v115, 0x4f800000, v114
	s_nop 0
	v_cndmask_b32_e32 v114, v114, v115, vcc
	v_sqrt_f32_e32 v115, v114
	s_nop 0
	v_add_u32_e32 v117, -1, v115
	v_fma_f32 v118, -v117, v115, v114
	v_cmp_ge_f32_e64 s[6:7], 0, v118
	v_add_u32_e32 v118, 1, v115
	s_nop 0
	v_cndmask_b32_e64 v117, v115, v117, s[6:7]
	v_fma_f32 v115, -v118, v115, v114
	v_cmp_lt_f32_e64 s[6:7], 0, v115
	s_nop 1
	v_cndmask_b32_e64 v115, v117, v118, s[6:7]
	v_mul_f32_e32 v117, 0x37800000, v115
	v_cndmask_b32_e32 v115, v115, v117, vcc
	v_cmp_class_f32_e32 vcc, v114, v174
	s_nop 1
	v_cndmask_b32_e32 v114, v115, v114, vcc
	v_div_scale_f32 v115, s[6:7], v114, v114, 1.0
	v_rcp_f32_e32 v117, v115
	s_nop 0
	v_fma_f32 v118, -v115, v117, 1.0
	v_fmac_f32_e32 v117, v118, v117
	v_div_scale_f32 v118, vcc, 1.0, v114, 1.0
	v_mul_f32_e32 v119, v118, v117
	v_fma_f32 v120, -v115, v119, v118
	v_fmac_f32_e32 v119, v120, v117
	v_fma_f32 v115, -v115, v119, v118
	v_div_fmas_f32 v115, v115, v117, v119
	v_div_fixup_f32 v120, v115, v114, 1.0
	v_ashrrev_i32_e32 v114, 31, v116
	v_mul_lo_u32 v115, s9, v116
	v_mul_lo_u32 v114, s8, v114
	v_mad_u64_u32 v[116:117], s[6:7], s8, v116, 0
	v_add3_u32 v117, v117, v114, v115
	s_and_b64 s[6:7], s[80:81], s[34:35]
	v_mov_b32_e32 v121, v120
	v_lshl_add_u64 v[118:119], v[116:117], 1, s[10:11]
	s_and_b64 vcc, exec, s[6:7]
	s_cbranch_vccnz .LBB0_418
	v_mov_b32_e32 v114, v120
	v_mov_b32_e32 v115, v120
	v_pk_mul_f32 v[124:125], v[112:113], v[114:115]
	v_pk_mul_f32 v[128:129], v[110:111], v[120:121]
	v_pk_mul_f32 v[122:123], v[108:109], v[114:115]
	v_pk_mul_f32 v[126:127], v[106:107], v[120:121]
	s_andn2_b64 vcc, exec, s[12:13]
	s_mov_b64 s[6:7], -1
	s_cbranch_vccnz .LBB0_416
	s_andn2_b64 vcc, exec, s[58:59]
	s_cbranch_vccnz .LBB0_413
	v_cvt_pk_bf16_f32 v106, v128, v129
	v_cvt_pk_bf16_f32 v107, v124, v125
	v_cvt_pk_bf16_f32 v108, v126, v127
	s_mov_b64 s[6:7], 0
	v_mov_b32_e32 v111, v123
	v_mov_b32_e32 v110, v122

;     __device__ __forceinline__ void operator()(const f32x4 (&acc)[2][2][4][2], const Unit& u, int wr, int wc, int fr, int fq) const {
;     ...
;             for (int m = 0; m < 4; ++m) {
;                 const int r = u.pm * BM + ai * HALF + wr * 64 + m * 16 + fr;
;                 if (u.pm * BM + ai * HALF + wr * 64 + m * 16 >= 16400) continue;
;                 const int drow = espace ? (r < 16384 ? r + 64 : r - 16384 + 48) : r;
;                 const float rs = 1.0f / sqrtf(stat[r] * (1.0f / 4096.0f) + 1e-6f);
; #pragma unroll
;                 for (int bj = 0; bj < 2; ++bj) {
;                     const int c = bj * HALF + wc * 32 + 8 * fq;
;                     if (pn == 38 && c >= 64) continue;
;                     const f32x4 v0 = acc[ai][bj][m][0] * rs, v1 = acc[ai][bj][m][1] * rs;
.LBB0_434:
	v_ashrrev_i32_e32 v99, 31, v98
	v_lshl_add_u64 v[98:99], v[98:99], 2, s[14:15]
	s_nop 1
	v_mov_b32_e32 v98, v201
	v_fmamk_f32 v98, v98, 0x39800000, v173
	v_cmp_gt_f32_e32 vcc, s95, v98
	v_mul_f32_e32 v99, 0x4f800000, v98
	s_nop 0
	v_cndmask_b32_e32 v98, v98, v99, vcc
	v_sqrt_f32_e32 v99, v98
	s_nop 0
	v_add_u32_e32 v101, -1, v99
	v_fma_f32 v102, -v101, v99, v98
	v_cmp_ge_f32_e64 s[6:7], 0, v102
	v_add_u32_e32 v102, 1, v99
	s_nop 0
	v_cndmask_b32_e64 v101, v99, v101, s[6:7]
	v_fma_f32 v99, -v102, v99, v98
	v_cmp_lt_f32_e64 s[6:7], 0, v99
	s_nop 1
	v_cndmask_b32_e64 v99, v101, v102, s[6:7]
	v_mul_f32_e32 v101, 0x37800000, v99
	v_cndmask_b32_e32 v99, v99, v101, vcc
	v_cmp_class_f32_e32 vcc, v98, v174
	s_nop 1
	v_cndmask_b32_e32 v98, v99, v98, vcc
	v_div_scale_f32 v99, s[6:7], v98, v98, 1.0
	v_rcp_f32_e32 v101, v99
	s_nop 0
	v_fma_f32 v102, -v99, v101, 1.0
	v_fmac_f32_e32 v101, v102, v101
	v_div_scale_f32 v102, vcc, 1.0, v98, 1.0
	v_mul_f32_e32 v103, v102, v101
	v_fma_f32 v104, -v99, v103, v102
	v_fmac_f32_e32 v103, v104, v101
	v_fma_f32 v99, -v99, v103, v102
	v_div_fmas_f32 v99, v99, v101, v103
	v_div_fixup_f32 v104, v99, v98, 1.0
	v_ashrrev_i32_e32 v98, 31, v100
	v_mul_lo_u32 v99, s9, v100
	v_mul_lo_u32 v98, s8, v98
	v_mad_u64_u32 v[100:101], s[6:7], s8, v100, 0
	v_add3_u32 v101, v101, v98, v99
	s_and_b64 s[6:7], s[80:81], s[34:35]
	v_mov_b32_e32 v105, v104
	v_lshl_add_u64 v[102:103], v[100:101], 1, s[10:11]
	s_and_b64 vcc, exec, s[6:7]
	s_cbranch_vccnz .LBB0_443
	v_mov_b32_e32 v98, v104
	v_mov_b32_e32 v99, v104
	v_pk_mul_f32 v[108:109], v[96:97], v[98:99]
	v_pk_mul_f32 v[112:113], v[94:95], v[104:105]
	v_pk_mul_f32 v[106:107], v[92:93], v[98:99]
	v_pk_mul_f32 v[110:111], v[90:91], v[104:105]
	s_andn2_b64 vcc, exec, s[12:13]
	s_mov_b64 s[6:7], -1
	s_cbranch_vccnz .LBB0_441
	s_andn2_b64 vcc, exec, s[58:59]
	s_cbranch_vccnz .LBB0_438
	v_cvt_pk_bf16_f32 v90, v112, v113
	v_cvt_pk_bf16_f32 v91, v108, v109
	v_cvt_pk_bf16_f32 v92, v110, v111
	s_mov_b64 s[6:7], 0
	v_mov_b32_e32 v95, v107
	v_mov_b32_e32 v94, v106

;     __device__ __forceinline__ void operator()(const f32x4 (&acc)[2][2][4][2], const Unit& u, int wr, int wc, int fr, int fq) const {
;     ...
;             for (int m = 0; m < 4; ++m) {
;                 const int r = u.pm * BM + ai * HALF + wr * 64 + m * 16 + fr;
;                 if (u.pm * BM + ai * HALF + wr * 64 + m * 16 >= 16400) continue;
;                 const int drow = espace ? (r < 16384 ? r + 64 : r - 16384 + 48) : r;
;                 const float rs = 1.0f / sqrtf(stat[r] * (1.0f / 4096.0f) + 1e-6f);
; #pragma unroll
;                 for (int bj = 0; bj < 2; ++bj) {
;                     const int c = bj * HALF + wc * 32 + 8 * fq;
;                     if (pn == 38 && c >= 64) continue;
;                     const f32x4 v0 = acc[ai][bj][m][0] * rs, v1 = acc[ai][bj][m][1] * rs;
.LBB0_459:
	v_ashrrev_i32_e32 v83, 31, v82
	v_lshl_add_u64 v[82:83], v[82:83], 2, s[14:15]
	s_nop 1
	v_mov_b32_e32 v82, v202
	v_fmamk_f32 v82, v82, 0x39800000, v173
	v_cmp_gt_f32_e32 vcc, s95, v82
	v_mul_f32_e32 v83, 0x4f800000, v82
	s_nop 0
	v_cndmask_b32_e32 v82, v82, v83, vcc
	v_sqrt_f32_e32 v83, v82
	s_nop 0
	v_add_u32_e32 v85, -1, v83
	v_fma_f32 v86, -v85, v83, v82
	v_cmp_ge_f32_e64 s[6:7], 0, v86
	v_add_u32_e32 v86, 1, v83
	s_nop 0
	v_cndmask_b32_e64 v85, v83, v85, s[6:7]
	v_fma_f32 v83, -v86, v83, v82
	v_cmp_lt_f32_e64 s[6:7], 0, v83
	s_nop 1
	v_cndmask_b32_e64 v83, v85, v86, s[6:7]
	v_mul_f32_e32 v85, 0x37800000, v83
	v_cndmask_b32_e32 v83, v83, v85, vcc
	v_cmp_class_f32_e32 vcc, v82, v174
	s_nop 1
	v_cndmask_b32_e32 v82, v83, v82, vcc
	v_div_scale_f32 v83, s[6:7], v82, v82, 1.0
	v_rcp_f32_e32 v85, v83
	s_nop 0
	v_fma_f32 v86, -v83, v85, 1.0
	v_fmac_f32_e32 v85, v86, v85
	v_div_scale_f32 v86, vcc, 1.0, v82, 1.0
	v_mul_f32_e32 v87, v86, v85
	v_fma_f32 v88, -v83, v87, v86
	v_fmac_f32_e32 v87, v88, v85
	v_fma_f32 v83, -v83, v87, v86
	v_div_fmas_f32 v83, v83, v85, v87
	v_div_fixup_f32 v88, v83, v82, 1.0
	v_ashrrev_i32_e32 v82, 31, v84
	v_mul_lo_u32 v83, s9, v84
	v_mul_lo_u32 v82, s8, v82
	v_mad_u64_u32 v[84:85], s[6:7], s8, v84, 0
	v_add3_u32 v85, v85, v82, v83
	s_and_b64 s[6:7], s[80:81], s[34:35]
	v_mov_b32_e32 v89, v88
	v_lshl_add_u64 v[86:87], v[84:85], 1, s[10:11]
	s_and_b64 vcc, exec, s[6:7]
	s_cbranch_vccnz .LBB0_468
	v_mov_b32_e32 v82, v88
	v_mov_b32_e32 v83, v88
	v_pk_mul_f32 v[92:93], v[80:81], v[82:83]
	v_pk_mul_f32 v[96:97], v[78:79], v[88:89]
	v_pk_mul_f32 v[90:91], v[76:77], v[82:83]
	v_pk_mul_f32 v[94:95], v[74:75], v[88:89]
	s_andn2_b64 vcc, exec, s[12:13]
	s_mov_b64 s[6:7], -1
	s_cbranch_vccnz .LBB0_466
	s_andn2_b64 vcc, exec, s[58:59]
	s_cbranch_vccnz .LBB0_463
	v_cvt_pk_bf16_f32 v74, v96, v97
	v_cvt_pk_bf16_f32 v75, v92, v93
	v_cvt_pk_bf16_f32 v76, v94, v95
	s_mov_b64 s[6:7], 0
	v_mov_b32_e32 v79, v91
	v_mov_b32_e32 v78, v90

;     __device__ __forceinline__ void operator()(const f32x4 (&acc)[2][2][4][2], const Unit& u, int wr, int wc, int fr, int fq) const {
;     ...
;             for (int m = 0; m < 4; ++m) {
;                 const int r = u.pm * BM + ai * HALF + wr * 64 + m * 16 + fr;
;                 if (u.pm * BM + ai * HALF + wr * 64 + m * 16 >= 16400) continue;
;                 const int drow = espace ? (r < 16384 ? r + 64 : r - 16384 + 48) : r;
;                 const float rs = 1.0f / sqrtf(stat[r] * (1.0f / 4096.0f) + 1e-6f);
; #pragma unroll
;                 for (int bj = 0; bj < 2; ++bj) {
;                     const int c = bj * HALF + wc * 32 + 8 * fq;
;                     if (pn == 38 && c >= 64) continue;
;                     const f32x4 v0 = acc[ai][bj][m][0] * rs, v1 = acc[ai][bj][m][1] * rs;
.LBB0_484:
	v_ashrrev_i32_e32 v67, 31, v66
	v_lshl_add_u64 v[66:67], v[66:67], 2, s[14:15]
	s_nop 1
	v_mov_b32_e32 v66, v203
	v_fmamk_f32 v66, v66, 0x39800000, v173
	v_cmp_gt_f32_e32 vcc, s95, v66
	v_mul_f32_e32 v67, 0x4f800000, v66
	s_nop 0
	v_cndmask_b32_e32 v66, v66, v67, vcc
	v_sqrt_f32_e32 v67, v66
	s_nop 0
	v_add_u32_e32 v69, -1, v67
	v_fma_f32 v70, -v69, v67, v66
	v_cmp_ge_f32_e64 s[6:7], 0, v70
	v_add_u32_e32 v70, 1, v67
	s_nop 0
	v_cndmask_b32_e64 v69, v67, v69, s[6:7]
	v_fma_f32 v67, -v70, v67, v66
	v_cmp_lt_f32_e64 s[6:7], 0, v67
	s_nop 1
	v_cndmask_b32_e64 v67, v69, v70, s[6:7]
	v_mul_f32_e32 v69, 0x37800000, v67
	v_cndmask_b32_e32 v67, v67, v69, vcc
	v_cmp_class_f32_e32 vcc, v66, v174
	s_nop 1
	v_cndmask_b32_e32 v66, v67, v66, vcc
	v_div_scale_f32 v67, s[6:7], v66, v66, 1.0
	v_rcp_f32_e32 v69, v67
	s_nop 0
	v_fma_f32 v70, -v67, v69, 1.0
	v_fmac_f32_e32 v69, v70, v69
	v_div_scale_f32 v70, vcc, 1.0, v66, 1.0
	v_mul_f32_e32 v71, v70, v69
	v_fma_f32 v72, -v67, v71, v70
	v_fmac_f32_e32 v71, v72, v69
	v_fma_f32 v67, -v67, v71, v70
	v_div_fmas_f32 v67, v67, v69, v71
	v_div_fixup_f32 v72, v67, v66, 1.0
	v_ashrrev_i32_e32 v66, 31, v68
	v_mul_lo_u32 v67, s9, v68
	v_mul_lo_u32 v66, s8, v66
	v_mad_u64_u32 v[68:69], s[6:7], s8, v68, 0
	v_add3_u32 v69, v69, v66, v67
	s_and_b64 s[6:7], s[80:81], s[34:35]
	v_mov_b32_e32 v73, v72
	v_lshl_add_u64 v[70:71], v[68:69], 1, s[10:11]
	s_and_b64 vcc, exec, s[6:7]
	s_cbranch_vccnz .LBB0_493
	v_mov_b32_e32 v66, v72
	v_mov_b32_e32 v67, v72
	v_pk_mul_f32 v[76:77], v[64:65], v[66:67]
	v_pk_mul_f32 v[80:81], v[62:63], v[72:73]
	v_pk_mul_f32 v[74:75], v[60:61], v[66:67]
	v_pk_mul_f32 v[78:79], v[58:59], v[72:73]
	s_andn2_b64 vcc, exec, s[12:13]
	s_mov_b64 s[6:7], -1
	s_cbranch_vccnz .LBB0_491
	s_andn2_b64 vcc, exec, s[58:59]
	s_cbranch_vccnz .LBB0_488
	v_cvt_pk_bf16_f32 v58, v80, v81
	v_cvt_pk_bf16_f32 v59, v76, v77
	v_cvt_pk_bf16_f32 v60, v78, v79
	s_mov_b64 s[6:7], 0
	v_mov_b32_e32 v63, v75
	v_mov_b32_e32 v62, v74

;     __device__ __forceinline__ void operator()(const f32x4 (&acc)[2][2][4][2], const Unit& u, int wr, int wc, int fr, int fq) const {
;     ...
;             for (int m = 0; m < 4; ++m) {
;                 const int r = u.pm * BM + ai * HALF + wr * 64 + m * 16 + fr;
;                 if (u.pm * BM + ai * HALF + wr * 64 + m * 16 >= 16400) continue;
;                 const int drow = espace ? (r < 16384 ? r + 64 : r - 16384 + 48) : r;
;                 const float rs = 1.0f / sqrtf(stat[r] * (1.0f / 4096.0f) + 1e-6f);
; #pragma unroll
;                 for (int bj = 0; bj < 2; ++bj) {
;                     const int c = bj * HALF + wc * 32 + 8 * fq;
;                     if (pn == 38 && c >= 64) continue;
;                     const f32x4 v0 = acc[ai][bj][m][0] * rs, v1 = acc[ai][bj][m][1] * rs;
.LBB0_509:
	v_ashrrev_i32_e32 v51, 31, v50
	v_lshl_add_u64 v[50:51], v[50:51], 2, s[14:15]
	s_nop 1
	v_mov_b32_e32 v50, v204
	v_fmamk_f32 v50, v50, 0x39800000, v173
	v_cmp_gt_f32_e32 vcc, s95, v50
	v_mul_f32_e32 v51, 0x4f800000, v50
	s_nop 0
	v_cndmask_b32_e32 v50, v50, v51, vcc
	v_sqrt_f32_e32 v51, v50
	s_nop 0
	v_add_u32_e32 v53, -1, v51
	v_fma_f32 v54, -v53, v51, v50
	v_cmp_ge_f32_e64 s[6:7], 0, v54
	v_add_u32_e32 v54, 1, v51
	s_nop 0
	v_cndmask_b32_e64 v53, v51, v53, s[6:7]
	v_fma_f32 v51, -v54, v51, v50
	v_cmp_lt_f32_e64 s[6:7], 0, v51
	s_nop 1
	v_cndmask_b32_e64 v51, v53, v54, s[6:7]
	v_mul_f32_e32 v53, 0x37800000, v51
	v_cndmask_b32_e32 v51, v51, v53, vcc
	v_cmp_class_f32_e32 vcc, v50, v174
	s_nop 1
	v_cndmask_b32_e32 v50, v51, v50, vcc
	v_div_scale_f32 v51, s[6:7], v50, v50, 1.0
	v_rcp_f32_e32 v53, v51
	s_nop 0
	v_fma_f32 v54, -v51, v53, 1.0
	v_fmac_f32_e32 v53, v54, v53
	v_div_scale_f32 v54, vcc, 1.0, v50, 1.0
	v_mul_f32_e32 v55, v54, v53
	v_fma_f32 v56, -v51, v55, v54
	v_fmac_f32_e32 v55, v56, v53
	v_fma_f32 v51, -v51, v55, v54
	v_div_fmas_f32 v51, v51, v53, v55
	v_div_fixup_f32 v56, v51, v50, 1.0
	v_ashrrev_i32_e32 v50, 31, v52
	v_mul_lo_u32 v51, s9, v52
	v_mul_lo_u32 v50, s8, v50
	v_mad_u64_u32 v[52:53], s[6:7], s8, v52, 0
	v_add3_u32 v53, v53, v50, v51
	s_and_b64 s[6:7], s[80:81], s[34:35]
	v_mov_b32_e32 v57, v56
	v_lshl_add_u64 v[54:55], v[52:53], 1, s[10:11]
	s_and_b64 vcc, exec, s[6:7]
	s_cbranch_vccnz .LBB0_518
	v_mov_b32_e32 v50, v56
	v_mov_b32_e32 v51, v56
	v_pk_mul_f32 v[60:61], v[48:49], v[50:51]
	v_pk_mul_f32 v[64:65], v[46:47], v[56:57]
	v_pk_mul_f32 v[58:59], v[44:45], v[50:51]
	v_pk_mul_f32 v[62:63], v[42:43], v[56:57]
	s_andn2_b64 vcc, exec, s[12:13]
	s_mov_b64 s[6:7], -1
	s_cbranch_vccnz .LBB0_516
	s_andn2_b64 vcc, exec, s[58:59]
	s_cbranch_vccnz .LBB0_513
	v_cvt_pk_bf16_f32 v42, v64, v65
	v_cvt_pk_bf16_f32 v43, v60, v61
	v_cvt_pk_bf16_f32 v44, v62, v63
	s_mov_b64 s[6:7], 0
	v_mov_b32_e32 v47, v59
	v_mov_b32_e32 v46, v58

;     __device__ __forceinline__ void operator()(const f32x4 (&acc)[2][2][4][2], const Unit& u, int wr, int wc, int fr, int fq) const {
;     ...
;             for (int m = 0; m < 4; ++m) {
;                 const int r = u.pm * BM + ai * HALF + wr * 64 + m * 16 + fr;
;                 if (u.pm * BM + ai * HALF + wr * 64 + m * 16 >= 16400) continue;
;                 const int drow = espace ? (r < 16384 ? r + 64 : r - 16384 + 48) : r;
;                 const float rs = 1.0f / sqrtf(stat[r] * (1.0f / 4096.0f) + 1e-6f);
; #pragma unroll
;                 for (int bj = 0; bj < 2; ++bj) {
;                     const int c = bj * HALF + wc * 32 + 8 * fq;
;                     if (pn == 38 && c >= 64) continue;
;                     const f32x4 v0 = acc[ai][bj][m][0] * rs, v1 = acc[ai][bj][m][1] * rs;
.LBB0_534:
	v_ashrrev_i32_e32 v35, 31, v34
	v_lshl_add_u64 v[34:35], v[34:35], 2, s[14:15]
	s_nop 1
	v_mov_b32_e32 v34, v205
	v_fmamk_f32 v34, v34, 0x39800000, v173
	v_cmp_gt_f32_e32 vcc, s95, v34
	v_mul_f32_e32 v35, 0x4f800000, v34
	s_nop 0
	v_cndmask_b32_e32 v34, v34, v35, vcc
	v_sqrt_f32_e32 v35, v34
	s_nop 0
	v_add_u32_e32 v37, -1, v35
	v_fma_f32 v38, -v37, v35, v34
	v_cmp_ge_f32_e64 s[6:7], 0, v38
	v_add_u32_e32 v38, 1, v35
	s_nop 0
	v_cndmask_b32_e64 v37, v35, v37, s[6:7]
	v_fma_f32 v35, -v38, v35, v34
	v_cmp_lt_f32_e64 s[6:7], 0, v35
	s_nop 1
	v_cndmask_b32_e64 v35, v37, v38, s[6:7]
	v_mul_f32_e32 v37, 0x37800000, v35
	v_cndmask_b32_e32 v35, v35, v37, vcc
	v_cmp_class_f32_e32 vcc, v34, v174
	s_nop 1
	v_cndmask_b32_e32 v34, v35, v34, vcc
	v_div_scale_f32 v35, s[6:7], v34, v34, 1.0
	v_rcp_f32_e32 v37, v35
	s_nop 0
	v_fma_f32 v38, -v35, v37, 1.0
	v_fmac_f32_e32 v37, v38, v37
	v_div_scale_f32 v38, vcc, 1.0, v34, 1.0
	v_mul_f32_e32 v39, v38, v37
	v_fma_f32 v40, -v35, v39, v38
	v_fmac_f32_e32 v39, v40, v37
	v_fma_f32 v35, -v35, v39, v38
	v_div_fmas_f32 v35, v35, v37, v39
	v_div_fixup_f32 v40, v35, v34, 1.0
	v_ashrrev_i32_e32 v34, 31, v36
	v_mul_lo_u32 v35, s9, v36
	v_mul_lo_u32 v34, s8, v34
	v_mad_u64_u32 v[36:37], s[6:7], s8, v36, 0
	v_add3_u32 v37, v37, v34, v35
	s_and_b64 s[6:7], s[80:81], s[34:35]
	v_mov_b32_e32 v41, v40
	v_lshl_add_u64 v[38:39], v[36:37], 1, s[10:11]
	s_and_b64 vcc, exec, s[6:7]
	s_cbranch_vccnz .LBB0_543
	v_mov_b32_e32 v34, v40
	v_mov_b32_e32 v35, v40
	v_pk_mul_f32 v[44:45], v[32:33], v[34:35]
	v_pk_mul_f32 v[48:49], v[30:31], v[40:41]
	v_pk_mul_f32 v[42:43], v[28:29], v[34:35]
	v_pk_mul_f32 v[46:47], v[26:27], v[40:41]
	s_andn2_b64 vcc, exec, s[12:13]
	s_mov_b64 s[6:7], -1
	s_cbranch_vccnz .LBB0_541
	s_andn2_b64 vcc, exec, s[58:59]
	s_cbranch_vccnz .LBB0_538
	v_cvt_pk_bf16_f32 v26, v48, v49
	v_cvt_pk_bf16_f32 v27, v44, v45
	v_cvt_pk_bf16_f32 v28, v46, v47
	s_mov_b64 s[6:7], 0
	v_mov_b32_e32 v31, v43
	v_mov_b32_e32 v30, v42

;     __device__ __forceinline__ void operator()(const f32x4 (&acc)[2][2][4][2], const Unit& u, int wr, int wc, int fr, int fq) const {
;     ...
;             for (int m = 0; m < 4; ++m) {
;                 const int r = u.pm * BM + ai * HALF + wr * 64 + m * 16 + fr;
;                 if (u.pm * BM + ai * HALF + wr * 64 + m * 16 >= 16400) continue;
;                 const int drow = espace ? (r < 16384 ? r + 64 : r - 16384 + 48) : r;
;                 const float rs = 1.0f / sqrtf(stat[r] * (1.0f / 4096.0f) + 1e-6f);
; #pragma unroll
;                 for (int bj = 0; bj < 2; ++bj) {
;                     const int c = bj * HALF + wc * 32 + 8 * fq;
;                     if (pn == 38 && c >= 64) continue;
;                     const f32x4 v0 = acc[ai][bj][m][0] * rs, v1 = acc[ai][bj][m][1] * rs;
.LBB0_559:
	v_ashrrev_i32_e32 v19, 31, v18
	v_lshl_add_u64 v[18:19], v[18:19], 2, s[14:15]
	s_nop 1
	v_mad_u64_u32 v[18:19], s[4:5], s8, v20, 0
	v_ashrrev_i32_e32 v22, 31, v20
	v_mul_lo_u32 v23, s9, v20
	s_and_b64 s[4:5], s[80:81], s[34:35]
	v_cndmask_b32_e64 v20, 0, 1, s[12:13]
	v_mul_lo_u32 v22, s8, v22
	s_and_b64 s[6:7], exec, s[4:5]
	v_cmp_ne_u32_e64 s[4:5], 1, v20
	v_add3_u32 v19, v19, v22, v23
	v_mov_b32_e32 v21, v206
	v_fmamk_f32 v21, v21, 0x39800000, v173
	v_mul_f32_e32 v24, 0x4f800000, v21
	v_cmp_gt_f32_e32 vcc, s95, v21
	s_nop 1
	v_cndmask_b32_e32 v21, v21, v24, vcc
	v_sqrt_f32_e32 v24, v21
	s_nop 0
	v_add_u32_e32 v20, -1, v24
	v_add_u32_e32 v22, 1, v24
	v_fma_f32 v23, -v20, v24, v21
	v_fma_f32 v25, -v22, v24, v21
	v_cmp_ge_f32_e64 s[8:9], 0, v23
	s_nop 1
	v_cndmask_b32_e64 v20, v24, v20, s[8:9]
	v_cmp_lt_f32_e64 s[8:9], 0, v25
	s_nop 1
	v_cndmask_b32_e64 v20, v20, v22, s[8:9]
	v_mul_f32_e32 v22, 0x37800000, v20
	v_cndmask_b32_e32 v20, v20, v22, vcc
	v_cmp_class_f32_e32 vcc, v21, v174
	s_nop 1
	v_cndmask_b32_e32 v22, v20, v21, vcc
	v_div_scale_f32 v23, s[8:9], v22, v22, 1.0
	v_rcp_f32_e32 v24, v23
	v_div_scale_f32 v25, vcc, 1.0, v22, 1.0
	v_lshl_add_u64 v[20:21], v[18:19], 1, s[10:11]
	v_fma_f32 v26, -v23, v24, 1.0
	v_fmac_f32_e32 v24, v26, v24
	v_mul_f32_e32 v26, v25, v24
	v_fma_f32 v27, -v23, v26, v25
	v_fmac_f32_e32 v26, v27, v24
	v_fma_f32 v23, -v23, v26, v25
	v_div_fmas_f32 v23, v23, v24, v26
	v_div_fixup_f32 v22, v23, v22, 1.0
	v_mov_b32_e32 v23, v22
	s_mov_b64 vcc, s[6:7]
	s_cbranch_vccnz .LBB0_568
	v_mov_b32_e32 v24, v22
	v_mov_b32_e32 v25, v22
	v_pk_mul_f32 v[16:17], v[16:17], v[24:25]
	v_pk_mul_f32 v[26:27], v[14:15], v[22:23]
	v_pk_mul_f32 v[14:15], v[12:13], v[24:25]
	v_pk_mul_f32 v[24:25], v[10:11], v[22:23]
	s_and_b64 vcc, exec, s[4:5]
	s_mov_b64 s[6:7], -1
	s_cbranch_vccnz .LBB0_566
	s_andn2_b64 vcc, exec, s[58:59]
	s_cbranch_vccnz .LBB0_563
	v_cvt_pk_bf16_f32 v10, v26, v27
	v_cvt_pk_bf16_f32 v11, v16, v17
	v_cvt_pk_bf16_f32 v12, v24, v25
	s_mov_b64 s[6:7], 0
	v_mov_b32_e32 v29, v15
	v_mov_b32_e32 v28, v14
